# neighbourhood attention: V^T tile of a half-block staged once through LDS by LDS-DMA (swizzled), PV fragments read from LDS instead of per-wave 16-row gathers
# speedup vs baseline: 1.1482x; 1.0070x over previous
.LBB0_1072:
	s_cmp_gt_i32 s66, 1
	s_mov_b64 s[0:1], -1
	s_cbranch_scc0 .LBB0_1115
	s_mov_b64 exec, -1
	v_writelane_b32 v245, s0, 0
	v_writelane_b32 v245, s1, 1
	v_writelane_b32 v245, s2, 2
	v_writelane_b32 v245, s3, 3
	v_writelane_b32 v245, s4, 4
	v_writelane_b32 v245, s5, 5
	v_writelane_b32 v245, s6, 6
	v_writelane_b32 v245, s7, 7
	v_writelane_b32 v245, s8, 8
	v_writelane_b32 v245, s9, 9
	v_writelane_b32 v245, s10, 10
	v_writelane_b32 v245, s11, 11
	v_writelane_b32 v245, s12, 12
	v_writelane_b32 v245, s13, 13
	v_writelane_b32 v245, s14, 14
	v_writelane_b32 v245, s15, 15
	v_writelane_b32 v245, s16, 16
	v_writelane_b32 v245, s17, 17
	v_writelane_b32 v245, s18, 18
	v_writelane_b32 v245, s19, 19
	v_writelane_b32 v245, s20, 20
	v_writelane_b32 v245, s21, 21
	v_writelane_b32 v245, s22, 22
	v_writelane_b32 v245, s23, 23
	v_writelane_b32 v245, s24, 24
	v_writelane_b32 v245, s25, 25
	v_writelane_b32 v245, s26, 26
	v_writelane_b32 v245, s27, 27
	v_writelane_b32 v245, s28, 28
	v_writelane_b32 v245, s29, 29
	v_writelane_b32 v245, s30, 30
	v_writelane_b32 v245, s31, 31
	v_writelane_b32 v245, s32, 32
	v_writelane_b32 v245, s33, 33
	v_writelane_b32 v245, s34, 34
	v_writelane_b32 v245, s35, 35
	v_writelane_b32 v245, s36, 36
	v_writelane_b32 v245, s37, 37
	v_writelane_b32 v245, s38, 38
	v_writelane_b32 v245, s39, 39
	v_writelane_b32 v245, s40, 40
	v_writelane_b32 v245, s41, 41
	v_writelane_b32 v245, s42, 42
	v_writelane_b32 v245, s43, 43
	v_writelane_b32 v245, s44, 44
	v_writelane_b32 v245, s45, 45
	v_writelane_b32 v245, s46, 46
	v_writelane_b32 v245, s47, 47
	v_writelane_b32 v245, s48, 48
	v_writelane_b32 v245, s49, 49
	v_writelane_b32 v245, s50, 50
	v_writelane_b32 v245, s51, 51
	v_writelane_b32 v245, s52, 52
	v_writelane_b32 v245, s53, 53
	v_writelane_b32 v245, s54, 54
	v_writelane_b32 v245, s55, 55
	v_writelane_b32 v245, s56, 56
	v_writelane_b32 v245, s57, 57
	v_writelane_b32 v245, s58, 58
	v_writelane_b32 v245, s59, 59
	v_writelane_b32 v245, s60, 60
	v_writelane_b32 v245, s61, 61
	v_writelane_b32 v245, s62, 62
	v_writelane_b32 v245, s63, 63
	v_writelane_b32 v244, s64, 0
	v_writelane_b32 v244, s65, 1
	v_writelane_b32 v244, s66, 2
	v_writelane_b32 v244, s67, 3
	v_writelane_b32 v244, s68, 4
	v_writelane_b32 v244, s69, 5
	v_writelane_b32 v244, s70, 6
	v_writelane_b32 v244, s71, 7
	v_writelane_b32 v244, s72, 8
	v_writelane_b32 v244, s73, 9
	v_writelane_b32 v244, s74, 10
	v_writelane_b32 v244, s75, 11
	v_writelane_b32 v244, s76, 12
	v_writelane_b32 v244, s77, 13
	v_writelane_b32 v244, s78, 14
	v_writelane_b32 v244, s79, 15
	v_lshrrev_b32_e32 v235, 6, v225
	v_and_b32_e32 v246, 63, v225
	s_load_dwordx2 s[10:11], s[100:101], 0xb0
	s_load_dwordx2 s[12:13], s[100:101], 0x28
	v_readfirstlane_b32 s4, v235
	v_and_b32_e32 v236, 15, v246
	v_lshrrev_b32_e32 v237, 4, v246
	s_nop 3
	s_and_b32 s5, s4, 3
	s_lshr_b32 s6, s4, 2
	s_lshl_b32 s7, s99, 1
	s_add_u32 s7, s7, s6
	s_lshl_b32 s8, s5, 4
	s_sub_i32 s8, s8, 8
	s_max_i32 s8, s8, 0
	s_min_i32 s8, s8, 32
	s_lshl_b32 s9, s5, 4
	v_lshrrev_b32_e32 v240, 2, v236
	v_and_b32_e32 v241, 3, v236
	v_lshl_add_u32 v240, v240, 3, v241
	v_lshlrev_b32_e32 v240, 10, v240
	v_lshl_add_u32 v218, v237, 4, v240
	v_add_u32_e32 v219, 0x1000, v218
	v_lshlrev_b32_e32 v240, 12, v236
	v_lshl_add_u32 v220, v237, 4, v240
	v_lshlrev_b32_e32 v240, 10, v236
	v_lshl_add_u32 v221, v237, 4, v240
	v_mul_u32_u24_e32 v240, 0xc00, v236
	v_lshl_add_u32 v222, v237, 3, v240
	v_xor_b32_e32 v223, 16, v246
	v_lshlrev_b32_e32 v223, 2, v223
	v_xor_b32_e32 v232, 32, v246
	v_lshlrev_b32_e32 v232, 2, v232
	s_lshr_b32 s36, s8, 3
	v_add_u32_e32 v136, s36, v237
	v_xor_b32_e32 v136, v136, v236
	v_lshlrev_b32_e32 v136, 4, v136
	v_lshl_or_b32 v136, v236, 10, v136
	s_lshl_b32 s36, s6, 16
	v_or_b32_e32 v136, s36, v136
	s_lshl_b32 s39, s5, 14
	s_add_u32 s39, s39, s36
	s_add_u32 s39, s39, 16
	v_add_u32_e32 v240, s9, v236
	v_lshl_add_u32 v241, v237, 3, s8
	v_sub_u32_e32 v235, v241, v240
	v_subrev_u32_e32 v240, 8, v240
	v_med3_i32 v240, v240, 0, 48
	v_sub_u32_e32 v241, v241, v240
	v_add_u32_e32 v240, 0, v235
	v_med3_i32 v240, v240, -15, 15
	v_add_u32_e32 v240, 15, v240
	v_lshlrev_b32_e32 v210, 2, v240
	v_add_u32_e32 v240, 0, v241
	v_cmp_gt_u32_e64 s[40:41], 16, v240
	v_add_u32_e32 v240, 1, v235
	v_med3_i32 v240, v240, -15, 15
	v_add_u32_e32 v240, 15, v240
	v_lshlrev_b32_e32 v211, 2, v240
	v_add_u32_e32 v240, 1, v241
	v_cmp_gt_u32_e64 s[42:43], 16, v240
	v_add_u32_e32 v240, 2, v235
	v_med3_i32 v240, v240, -15, 15
	v_add_u32_e32 v240, 15, v240
	v_lshlrev_b32_e32 v212, 2, v240
	v_add_u32_e32 v240, 2, v241
	v_cmp_gt_u32_e64 s[44:45], 16, v240
	v_add_u32_e32 v240, 3, v235
	v_med3_i32 v240, v240, -15, 15
	v_add_u32_e32 v240, 15, v240
	v_lshlrev_b32_e32 v213, 2, v240
	v_add_u32_e32 v240, 3, v241
	v_cmp_gt_u32_e64 s[46:47], 16, v240
	v_add_u32_e32 v240, 4, v235
	v_med3_i32 v240, v240, -15, 15
	v_add_u32_e32 v240, 15, v240
	v_lshlrev_b32_e32 v214, 2, v240
	v_add_u32_e32 v240, 4, v241
	v_cmp_gt_u32_e64 s[48:49], 16, v240
	v_add_u32_e32 v240, 5, v235
	v_med3_i32 v240, v240, -15, 15
	v_add_u32_e32 v240, 15, v240
	v_lshlrev_b32_e32 v215, 2, v240
	v_add_u32_e32 v240, 5, v241
	v_cmp_gt_u32_e64 s[50:51], 16, v240
	v_add_u32_e32 v240, 6, v235
	v_med3_i32 v240, v240, -15, 15
	v_add_u32_e32 v240, 15, v240
	v_lshlrev_b32_e32 v216, 2, v240
	v_add_u32_e32 v240, 6, v241
	v_cmp_gt_u32_e64 s[52:53], 16, v240
	v_add_u32_e32 v240, 7, v235
	v_med3_i32 v240, v240, -15, 15
	v_add_u32_e32 v240, 15, v240
	v_lshlrev_b32_e32 v217, 2, v240
	v_add_u32_e32 v240, 7, v241
	v_cmp_gt_u32_e64 s[54:55], 16, v240
	s_waitcnt lgkmcnt(0)
	s_mov_b32 s14, 0
.Lna_tile:
	s_and_b32 s15, s7, 7
	s_bfe_u32 s16, s7, 0x50003
	s_lshr_b32 s17, s7, 8
	s_sub_i32 s18, s16, 4
	s_max_i32 s18, s18, 0
	s_min_i32 s18, s18, 24
	s_lshl_b32 s19, s17, 11
	s_lshl_b32 s20, s18, 6
	s_add_u32 s20, s20, s19
	s_add_u32 s20, s20, s8
	s_lshl_b32 s21, s16, 6
	s_add_u32 s21, s21, s19
	s_add_u32 s21, s21, s9
	s_lshl_b32 s22, s15, 7
	s_lshl_b32 s23, s20, 10
	s_add_u32 s23, s23, s22
	s_add_u32 s0, s10, 0x5200000
	s_addc_u32 s1, s11, 0
	s_add_u32 s0, s0, s23
	s_addc_u32 s1, s1, 0
	s_lshl_b32 s23, s17, 3
	s_add_u32 s23, s23, s15
	s_lshl_b32 s23, s23, 18
	s_lshl_b32 s24, s5, 16
	s_add_u32 s23, s23, s24
	s_lshl_b32 s24, s18, 7
	s_add_u32 s23, s23, s24
	s_add_u32 s24, s10, 0x6200000
	s_addc_u32 s25, s11, 0
	s_add_u32 s24, s24, s23
	s_addc_u32 s25, s25, 0
	s_lshl_b32 s23, s21, 10
	s_add_u32 s23, s23, s22
	s_add_u32 s2, s10, 0x4200000
	s_addc_u32 s3, s11, 0
	s_add_u32 s2, s2, s23
	s_addc_u32 s3, s3, 0
	s_mul_i32 s23, s21, 0xc00
	s_add_u32 s23, s23, s22
	s_add_u32 s32, s10, 0xc200000
	s_addc_u32 s33, s11, 0
	s_add_u32 s32, s32, s23
	s_addc_u32 s33, s33, 0
	s_mul_i32 s23, s15, 465
	s_sub_i32 s34, s18, s16
	s_add_i32 s34, s34, 7
	s_mul_i32 s34, s34, 31
	s_add_u32 s23, s23, s34
	s_lshl_b32 s23, s23, 2
	s_add_u32 s34, s12, s23
	s_addc_u32 s35, s13, 0
	s_barrier
	global_load_dwordx4 v[0:3], v221, s[2:3]
	global_load_dwordx4 v[4:7], v221, s[2:3] offset:64
	global_load_dwordx4 v[72:75], v218, s[0:1]
	global_load_dwordx4 v[76:79], v218, s[0:1] offset:64
	global_load_dwordx4 v[80:83], v219, s[0:1]
	global_load_dwordx4 v[84:87], v219, s[0:1] offset:64
	s_add_u32 s0, s0, 0x10000
	s_addc_u32 s1, s1, 0
	global_load_dword v8, v210, s[34:35]
	global_load_dword v9, v211, s[34:35]
	global_load_dword v10, v212, s[34:35]
	global_load_dword v11, v213, s[34:35]
	global_load_dword v12, v214, s[34:35]
	global_load_dword v13, v215, s[34:35]
	global_load_dword v14, v216, s[34:35]
	global_load_dword v15, v217, s[34:35]
	global_load_dwordx4 v[88:91], v218, s[0:1]
	global_load_dwordx4 v[92:95], v218, s[0:1] offset:64
	global_load_dwordx4 v[96:99], v219, s[0:1]
	global_load_dwordx4 v[100:103], v219, s[0:1] offset:64
	s_add_u32 s0, s0, 0x10000
	s_addc_u32 s1, s1, 0
	global_load_dword v16, v210, s[34:35] offset:124
	global_load_dword v17, v211, s[34:35] offset:124
	global_load_dword v18, v212, s[34:35] offset:124
	global_load_dword v19, v213, s[34:35] offset:124
	global_load_dword v20, v214, s[34:35] offset:124
	global_load_dword v21, v215, s[34:35] offset:124
	global_load_dword v22, v216, s[34:35] offset:124
	global_load_dword v23, v217, s[34:35] offset:124
	global_load_dwordx4 v[104:107], v218, s[0:1]
	global_load_dwordx4 v[108:111], v218, s[0:1] offset:64
	global_load_dwordx4 v[112:115], v219, s[0:1]
	global_load_dwordx4 v[116:119], v219, s[0:1] offset:64
	s_add_u32 s0, s0, 0x10000
	s_addc_u32 s1, s1, 0
	global_load_dword v24, v210, s[34:35] offset:248
	global_load_dword v25, v211, s[34:35] offset:248
	global_load_dword v26, v212, s[34:35] offset:248
	global_load_dword v27, v213, s[34:35] offset:248
	global_load_dword v28, v214, s[34:35] offset:248
	global_load_dword v29, v215, s[34:35] offset:248
	global_load_dword v30, v216, s[34:35] offset:248
	global_load_dword v31, v217, s[34:35] offset:248
	global_load_dwordx4 v[120:123], v218, s[0:1]
	global_load_dwordx4 v[124:127], v218, s[0:1] offset:64
	global_load_dwordx4 v[128:131], v219, s[0:1]
	global_load_dwordx4 v[132:135], v219, s[0:1] offset:64
	s_add_u32 s0, s0, 0x10000
	s_addc_u32 s1, s1, 0
	global_load_dword v32, v210, s[34:35] offset:372
	global_load_dword v33, v211, s[34:35] offset:372
	global_load_dword v34, v212, s[34:35] offset:372
	global_load_dword v35, v213, s[34:35] offset:372
	global_load_dword v36, v214, s[34:35] offset:372
	global_load_dword v37, v215, s[34:35] offset:372
	global_load_dword v38, v216, s[34:35] offset:372
	global_load_dword v39, v217, s[34:35] offset:372
	global_load_dwordx4 v[146:149], v218, s[0:1]
	global_load_dwordx4 v[150:153], v218, s[0:1] offset:64
	global_load_dwordx4 v[154:157], v219, s[0:1]
	global_load_dwordx4 v[158:161], v219, s[0:1] offset:64
	s_add_u32 s0, s0, 0x10000
	s_addc_u32 s1, s1, 0
	global_load_dword v40, v210, s[34:35] offset:496
	global_load_dword v41, v211, s[34:35] offset:496
	global_load_dword v42, v212, s[34:35] offset:496
	global_load_dword v43, v213, s[34:35] offset:496
	global_load_dword v44, v214, s[34:35] offset:496
	global_load_dword v45, v215, s[34:35] offset:496
	global_load_dword v46, v216, s[34:35] offset:496
	global_load_dword v47, v217, s[34:35] offset:496
	global_load_dwordx4 v[162:165], v218, s[0:1]
	global_load_dwordx4 v[166:169], v218, s[0:1] offset:64
	global_load_dwordx4 v[170:173], v219, s[0:1]
	global_load_dwordx4 v[174:177], v219, s[0:1] offset:64
	s_add_u32 s0, s0, 0x10000
	s_addc_u32 s1, s1, 0
	global_load_dword v48, v210, s[34:35] offset:620
	global_load_dword v49, v211, s[34:35] offset:620
	global_load_dword v50, v212, s[34:35] offset:620
	global_load_dword v51, v213, s[34:35] offset:620
	global_load_dword v52, v214, s[34:35] offset:620
	global_load_dword v53, v215, s[34:35] offset:620
	global_load_dword v54, v216, s[34:35] offset:620
	global_load_dword v55, v217, s[34:35] offset:620
	global_load_dword v56, v210, s[34:35] offset:744
	global_load_dword v57, v211, s[34:35] offset:744
	global_load_dword v58, v212, s[34:35] offset:744
	global_load_dword v59, v213, s[34:35] offset:744
	global_load_dword v60, v214, s[34:35] offset:744
	global_load_dword v61, v215, s[34:35] offset:744
	global_load_dword v62, v216, s[34:35] offset:744
	global_load_dword v63, v217, s[34:35] offset:744
	global_load_dword v64, v210, s[34:35] offset:868
	global_load_dword v65, v211, s[34:35] offset:868
	global_load_dword v66, v212, s[34:35] offset:868
	global_load_dword v67, v213, s[34:35] offset:868
	global_load_dword v68, v214, s[34:35] offset:868
	global_load_dword v69, v215, s[34:35] offset:868
	global_load_dword v70, v216, s[34:35] offset:868
	global_load_dword v71, v217, s[34:35] offset:868
	s_mov_b32 s26, s39
	v_xor_b32_e32 v137, 0, v246
	s_mov_b32 m0, s26
	v_lshlrev_b32_e32 v137, 4, v137
	global_load_lds_dwordx4 v137, s[24:25]
	s_add_u32 s24, s24, 0x1000
	s_addc_u32 s25, s25, 0
	s_add_u32 s26, s26, 0x400
	v_xor_b32_e32 v137, 1, v246
	s_mov_b32 m0, s26
	v_lshlrev_b32_e32 v137, 4, v137
	global_load_lds_dwordx4 v137, s[24:25]
	s_add_u32 s24, s24, 0x1000
	s_addc_u32 s25, s25, 0
	s_add_u32 s26, s26, 0x400
	v_xor_b32_e32 v137, 2, v246
	s_mov_b32 m0, s26
	v_lshlrev_b32_e32 v137, 4, v137
	global_load_lds_dwordx4 v137, s[24:25]
	s_add_u32 s24, s24, 0x1000
	s_addc_u32 s25, s25, 0
	s_add_u32 s26, s26, 0x400
	v_xor_b32_e32 v137, 3, v246
	s_mov_b32 m0, s26
	v_lshlrev_b32_e32 v137, 4, v137
	global_load_lds_dwordx4 v137, s[24:25]
	s_add_u32 s24, s24, 0x1000
	s_addc_u32 s25, s25, 0
	s_add_u32 s26, s26, 0x400
	v_xor_b32_e32 v137, 4, v246
	s_mov_b32 m0, s26
	v_lshlrev_b32_e32 v137, 4, v137
	global_load_lds_dwordx4 v137, s[24:25]
	s_add_u32 s24, s24, 0x1000
	s_addc_u32 s25, s25, 0
	s_add_u32 s26, s26, 0x400
	v_xor_b32_e32 v137, 5, v246
	s_mov_b32 m0, s26
	v_lshlrev_b32_e32 v137, 4, v137
	global_load_lds_dwordx4 v137, s[24:25]
	s_add_u32 s24, s24, 0x1000
	s_addc_u32 s25, s25, 0
	s_add_u32 s26, s26, 0x400
	v_xor_b32_e32 v137, 6, v246
	s_mov_b32 m0, s26
	v_lshlrev_b32_e32 v137, 4, v137
	global_load_lds_dwordx4 v137, s[24:25]
	s_add_u32 s24, s24, 0x1000
	s_addc_u32 s25, s25, 0
	s_add_u32 s26, s26, 0x400
	v_xor_b32_e32 v137, 7, v246
	s_mov_b32 m0, s26
	v_lshlrev_b32_e32 v137, 4, v137
	global_load_lds_dwordx4 v137, s[24:25]
	s_add_u32 s24, s24, 0x1000
	s_addc_u32 s25, s25, 0
	s_add_u32 s26, s26, 0x400
	v_xor_b32_e32 v137, 8, v246
	s_mov_b32 m0, s26
	v_lshlrev_b32_e32 v137, 4, v137
	global_load_lds_dwordx4 v137, s[24:25]
	s_add_u32 s24, s24, 0x1000
	s_addc_u32 s25, s25, 0
	s_add_u32 s26, s26, 0x400
	v_xor_b32_e32 v137, 9, v246
	s_mov_b32 m0, s26
	v_lshlrev_b32_e32 v137, 4, v137
	global_load_lds_dwordx4 v137, s[24:25]
	s_add_u32 s24, s24, 0x1000
	s_addc_u32 s25, s25, 0
	s_add_u32 s26, s26, 0x400
	v_xor_b32_e32 v137, 10, v246
	s_mov_b32 m0, s26
	v_lshlrev_b32_e32 v137, 4, v137
	global_load_lds_dwordx4 v137, s[24:25]
	s_add_u32 s24, s24, 0x1000
	s_addc_u32 s25, s25, 0
	s_add_u32 s26, s26, 0x400
	v_xor_b32_e32 v137, 11, v246
	s_mov_b32 m0, s26
	v_lshlrev_b32_e32 v137, 4, v137
	global_load_lds_dwordx4 v137, s[24:25]
	s_add_u32 s24, s24, 0x1000
	s_addc_u32 s25, s25, 0
	s_add_u32 s26, s26, 0x400
	v_xor_b32_e32 v137, 12, v246
	s_mov_b32 m0, s26
	v_lshlrev_b32_e32 v137, 4, v137
	global_load_lds_dwordx4 v137, s[24:25]
	s_add_u32 s24, s24, 0x1000
	s_addc_u32 s25, s25, 0
	s_add_u32 s26, s26, 0x400
	v_xor_b32_e32 v137, 13, v246
	s_mov_b32 m0, s26
	v_lshlrev_b32_e32 v137, 4, v137
	global_load_lds_dwordx4 v137, s[24:25]
	s_add_u32 s24, s24, 0x1000
	s_addc_u32 s25, s25, 0
	s_add_u32 s26, s26, 0x400
	v_xor_b32_e32 v137, 14, v246
	s_mov_b32 m0, s26
	v_lshlrev_b32_e32 v137, 4, v137
	global_load_lds_dwordx4 v137, s[24:25]
	s_add_u32 s24, s24, 0x1000
	s_addc_u32 s25, s25, 0
	s_add_u32 s26, s26, 0x400
	v_xor_b32_e32 v137, 15, v246
	s_mov_b32 m0, s26
	v_lshlrev_b32_e32 v137, 4, v137
	global_load_lds_dwordx4 v137, s[24:25]
	s_add_u32 s24, s24, 0x1000
	s_addc_u32 s25, s25, 0
	s_add_u32 s26, s26, 0x400
	v_mov_b32_e32 v178, 0
	v_mov_b32_e32 v179, 0
	v_mov_b32_e32 v180, 0
	v_mov_b32_e32 v181, 0
	v_mov_b32_e32 v182, 0
	v_mov_b32_e32 v183, 0
	v_mov_b32_e32 v184, 0
	v_mov_b32_e32 v185, 0
	v_mov_b32_e32 v186, 0
	v_mov_b32_e32 v187, 0
	v_mov_b32_e32 v188, 0
	v_mov_b32_e32 v189, 0
	v_mov_b32_e32 v190, 0
	v_mov_b32_e32 v191, 0
	v_mov_b32_e32 v192, 0
	v_mov_b32_e32 v193, 0
	s_waitcnt vmcnt(63)
	v_mfma_f32_16x16x32_bf16 v[194:197], v[72:75], v[0:3], 0
	v_mfma_f32_16x16x32_bf16 v[198:201], v[80:83], v[0:3], 0
	v_mfma_f32_16x16x32_bf16 v[194:197], v[76:79], v[4:7], v[194:197]
	v_mfma_f32_16x16x32_bf16 v[198:201], v[84:87], v[4:7], v[198:201]
	global_load_dwordx4 v[72:75], v218, s[0:1]
	global_load_dwordx4 v[76:79], v218, s[0:1] offset:64
	global_load_dwordx4 v[80:83], v219, s[0:1]
	global_load_dwordx4 v[84:87], v219, s[0:1] offset:64
	s_add_u32 s0, s0, 0x10000
	s_addc_u32 s1, s1, 0
	s_waitcnt vmcnt(63)
	v_mfma_f32_16x16x32_bf16 v[202:205], v[88:91], v[0:3], 0
	v_mfma_f32_16x16x32_bf16 v[206:209], v[96:99], v[0:3], 0
	v_mfma_f32_16x16x32_bf16 v[202:205], v[92:95], v[4:7], v[202:205]
	v_mfma_f32_16x16x32_bf16 v[206:209], v[100:103], v[4:7], v[206:209]
	global_load_dwordx4 v[88:91], v218, s[0:1]
	global_load_dwordx4 v[92:95], v218, s[0:1] offset:64
	global_load_dwordx4 v[96:99], v219, s[0:1]
	global_load_dwordx4 v[100:103], v219, s[0:1] offset:64
	s_add_u32 s0, s0, 0x10000
	s_addc_u32 s1, s1, 0
	s_waitcnt vmcnt(63)
	v_fmamk_f32 v235, v8, 0x3fb8aa3b, v194
	v_mov_b32_e32 v8, 0xff800000
	v_cndmask_b32_e64 v8, v8, v235, s[40:41]
	v_fmamk_f32 v235, v9, 0x3fb8aa3b, v195
	v_mov_b32_e32 v9, 0xff800000
	v_cndmask_b32_e64 v9, v9, v235, s[42:43]
	v_fmamk_f32 v235, v10, 0x3fb8aa3b, v196
	v_mov_b32_e32 v10, 0xff800000
	v_cndmask_b32_e64 v10, v10, v235, s[44:45]
	v_fmamk_f32 v235, v11, 0x3fb8aa3b, v197
	v_mov_b32_e32 v11, 0xff800000
	v_cndmask_b32_e64 v11, v11, v235, s[46:47]
	v_fmamk_f32 v235, v12, 0x3fb8aa3b, v198
	v_mov_b32_e32 v12, 0xff800000
	v_cndmask_b32_e64 v12, v12, v235, s[48:49]
	v_fmamk_f32 v235, v13, 0x3fb8aa3b, v199
	v_mov_b32_e32 v13, 0xff800000
	v_cndmask_b32_e64 v13, v13, v235, s[50:51]
	v_fmamk_f32 v235, v14, 0x3fb8aa3b, v200
	v_mov_b32_e32 v14, 0xff800000
	v_cndmask_b32_e64 v14, v14, v235, s[52:53]
	v_fmamk_f32 v235, v15, 0x3fb8aa3b, v201
	v_mov_b32_e32 v15, 0xff800000
	v_cndmask_b32_e64 v15, v15, v235, s[54:55]
	s_waitcnt vmcnt(63)
	v_mfma_f32_16x16x32_bf16 v[194:197], v[104:107], v[0:3], 0
	v_mfma_f32_16x16x32_bf16 v[198:201], v[112:115], v[0:3], 0
	v_mfma_f32_16x16x32_bf16 v[194:197], v[108:111], v[4:7], v[194:197]
	v_mfma_f32_16x16x32_bf16 v[198:201], v[116:119], v[4:7], v[198:201]
	s_waitcnt vmcnt(63)
	v_fmamk_f32 v235, v16, 0x3fb8aa3b, v202
	v_mov_b32_e32 v16, 0xff800000
	v_cndmask_b32_e64 v16, v16, v235, s[40:41]
	v_fmamk_f32 v235, v17, 0x3fb8aa3b, v203
	v_mov_b32_e32 v17, 0xff800000
	v_cndmask_b32_e64 v17, v17, v235, s[42:43]
	v_fmamk_f32 v235, v18, 0x3fb8aa3b, v204
	v_mov_b32_e32 v18, 0xff800000
	v_cndmask_b32_e64 v18, v18, v235, s[44:45]
	v_fmamk_f32 v235, v19, 0x3fb8aa3b, v205
	v_mov_b32_e32 v19, 0xff800000
	v_cndmask_b32_e64 v19, v19, v235, s[46:47]
	v_fmamk_f32 v235, v20, 0x3fb8aa3b, v206
	v_mov_b32_e32 v20, 0xff800000
	v_cndmask_b32_e64 v20, v20, v235, s[48:49]
	v_fmamk_f32 v235, v21, 0x3fb8aa3b, v207
	v_mov_b32_e32 v21, 0xff800000
	v_cndmask_b32_e64 v21, v21, v235, s[50:51]
	v_fmamk_f32 v235, v22, 0x3fb8aa3b, v208
	v_mov_b32_e32 v22, 0xff800000
	v_cndmask_b32_e64 v22, v22, v235, s[52:53]
	v_fmamk_f32 v235, v23, 0x3fb8aa3b, v209
	v_mov_b32_e32 v23, 0xff800000
	v_cndmask_b32_e64 v23, v23, v235, s[54:55]
	s_waitcnt vmcnt(63)
	v_mfma_f32_16x16x32_bf16 v[202:205], v[120:123], v[0:3], 0
	v_mfma_f32_16x16x32_bf16 v[206:209], v[128:131], v[0:3], 0
	v_mfma_f32_16x16x32_bf16 v[202:205], v[124:127], v[4:7], v[202:205]
	v_mfma_f32_16x16x32_bf16 v[206:209], v[132:135], v[4:7], v[206:209]
	s_waitcnt vmcnt(63)
	v_fmamk_f32 v235, v24, 0x3fb8aa3b, v194
	v_mov_b32_e32 v24, 0xff800000
	v_cndmask_b32_e64 v24, v24, v235, s[40:41]
	v_fmamk_f32 v235, v25, 0x3fb8aa3b, v195
	v_mov_b32_e32 v25, 0xff800000
	v_cndmask_b32_e64 v25, v25, v235, s[42:43]
	v_fmamk_f32 v235, v26, 0x3fb8aa3b, v196
	v_mov_b32_e32 v26, 0xff800000
	v_cndmask_b32_e64 v26, v26, v235, s[44:45]
	v_fmamk_f32 v235, v27, 0x3fb8aa3b, v197
	v_mov_b32_e32 v27, 0xff800000
	v_cndmask_b32_e64 v27, v27, v235, s[46:47]
	v_fmamk_f32 v235, v28, 0x3fb8aa3b, v198
	v_mov_b32_e32 v28, 0xff800000
	v_cndmask_b32_e64 v28, v28, v235, s[48:49]
	v_fmamk_f32 v235, v29, 0x3fb8aa3b, v199
	v_mov_b32_e32 v29, 0xff800000
	v_cndmask_b32_e64 v29, v29, v235, s[50:51]
	v_fmamk_f32 v235, v30, 0x3fb8aa3b, v200
	v_mov_b32_e32 v30, 0xff800000
	v_cndmask_b32_e64 v30, v30, v235, s[52:53]
	v_fmamk_f32 v235, v31, 0x3fb8aa3b, v201
	v_mov_b32_e32 v31, 0xff800000
	v_cndmask_b32_e64 v31, v31, v235, s[54:55]
	s_waitcnt vmcnt(60)
	v_mfma_f32_16x16x32_bf16 v[194:197], v[146:149], v[0:3], 0
	v_mfma_f32_16x16x32_bf16 v[198:201], v[154:157], v[0:3], 0
	v_mfma_f32_16x16x32_bf16 v[194:197], v[150:153], v[4:7], v[194:197]
	v_mfma_f32_16x16x32_bf16 v[198:201], v[158:161], v[4:7], v[198:201]
	s_waitcnt vmcnt(63)
	v_fmamk_f32 v235, v32, 0x3fb8aa3b, v202
	v_mov_b32_e32 v32, 0xff800000
	v_cndmask_b32_e64 v32, v32, v235, s[40:41]
	v_fmamk_f32 v235, v33, 0x3fb8aa3b, v203
	v_mov_b32_e32 v33, 0xff800000
	v_cndmask_b32_e64 v33, v33, v235, s[42:43]
	v_fmamk_f32 v235, v34, 0x3fb8aa3b, v204
	v_mov_b32_e32 v34, 0xff800000
	v_cndmask_b32_e64 v34, v34, v235, s[44:45]
	v_fmamk_f32 v235, v35, 0x3fb8aa3b, v205
	v_mov_b32_e32 v35, 0xff800000
	v_cndmask_b32_e64 v35, v35, v235, s[46:47]
	v_fmamk_f32 v235, v36, 0x3fb8aa3b, v206
	v_mov_b32_e32 v36, 0xff800000
	v_cndmask_b32_e64 v36, v36, v235, s[48:49]
	v_fmamk_f32 v235, v37, 0x3fb8aa3b, v207
	v_mov_b32_e32 v37, 0xff800000
	v_cndmask_b32_e64 v37, v37, v235, s[50:51]
	v_fmamk_f32 v235, v38, 0x3fb8aa3b, v208
	v_mov_b32_e32 v38, 0xff800000
	v_cndmask_b32_e64 v38, v38, v235, s[52:53]
	v_fmamk_f32 v235, v39, 0x3fb8aa3b, v209
	v_mov_b32_e32 v39, 0xff800000
	v_cndmask_b32_e64 v39, v39, v235, s[54:55]
	s_waitcnt vmcnt(48)
	v_mfma_f32_16x16x32_bf16 v[202:205], v[162:165], v[0:3], 0
	v_mfma_f32_16x16x32_bf16 v[206:209], v[170:173], v[0:3], 0
	v_mfma_f32_16x16x32_bf16 v[202:205], v[166:169], v[4:7], v[202:205]
	v_mfma_f32_16x16x32_bf16 v[206:209], v[174:177], v[4:7], v[206:209]
	s_waitcnt vmcnt(52)
	v_fmamk_f32 v235, v40, 0x3fb8aa3b, v194
	v_mov_b32_e32 v40, 0xff800000
	v_cndmask_b32_e64 v40, v40, v235, s[40:41]
	v_fmamk_f32 v235, v41, 0x3fb8aa3b, v195
	v_mov_b32_e32 v41, 0xff800000
	v_cndmask_b32_e64 v41, v41, v235, s[42:43]
	v_fmamk_f32 v235, v42, 0x3fb8aa3b, v196
	v_mov_b32_e32 v42, 0xff800000
	v_cndmask_b32_e64 v42, v42, v235, s[44:45]
	v_fmamk_f32 v235, v43, 0x3fb8aa3b, v197
	v_mov_b32_e32 v43, 0xff800000
	v_cndmask_b32_e64 v43, v43, v235, s[46:47]
	v_fmamk_f32 v235, v44, 0x3fb8aa3b, v198
	v_mov_b32_e32 v44, 0xff800000
	v_cndmask_b32_e64 v44, v44, v235, s[48:49]
	v_fmamk_f32 v235, v45, 0x3fb8aa3b, v199
	v_mov_b32_e32 v45, 0xff800000
	v_cndmask_b32_e64 v45, v45, v235, s[50:51]
	v_fmamk_f32 v235, v46, 0x3fb8aa3b, v200
	v_mov_b32_e32 v46, 0xff800000
	v_cndmask_b32_e64 v46, v46, v235, s[52:53]
	v_fmamk_f32 v235, v47, 0x3fb8aa3b, v201
	v_mov_b32_e32 v47, 0xff800000
	v_cndmask_b32_e64 v47, v47, v235, s[54:55]
	s_waitcnt vmcnt(4)
	v_mfma_f32_16x16x32_bf16 v[194:197], v[72:75], v[0:3], 0
	v_mfma_f32_16x16x32_bf16 v[198:201], v[80:83], v[0:3], 0
	v_mfma_f32_16x16x32_bf16 v[194:197], v[76:79], v[4:7], v[194:197]
	v_mfma_f32_16x16x32_bf16 v[198:201], v[84:87], v[4:7], v[198:201]
	s_waitcnt vmcnt(40)
	v_fmamk_f32 v235, v48, 0x3fb8aa3b, v202
	v_mov_b32_e32 v48, 0xff800000
	v_cndmask_b32_e64 v48, v48, v235, s[40:41]
	v_fmamk_f32 v235, v49, 0x3fb8aa3b, v203
	v_mov_b32_e32 v49, 0xff800000
	v_cndmask_b32_e64 v49, v49, v235, s[42:43]
	v_fmamk_f32 v235, v50, 0x3fb8aa3b, v204
	v_mov_b32_e32 v50, 0xff800000
	v_cndmask_b32_e64 v50, v50, v235, s[44:45]
	v_fmamk_f32 v235, v51, 0x3fb8aa3b, v205
	v_mov_b32_e32 v51, 0xff800000
	v_cndmask_b32_e64 v51, v51, v235, s[46:47]
	v_fmamk_f32 v235, v52, 0x3fb8aa3b, v206
	v_mov_b32_e32 v52, 0xff800000
	v_cndmask_b32_e64 v52, v52, v235, s[48:49]
	v_fmamk_f32 v235, v53, 0x3fb8aa3b, v207
	v_mov_b32_e32 v53, 0xff800000
	v_cndmask_b32_e64 v53, v53, v235, s[50:51]
	v_fmamk_f32 v235, v54, 0x3fb8aa3b, v208
	v_mov_b32_e32 v54, 0xff800000
	v_cndmask_b32_e64 v54, v54, v235, s[52:53]
	v_fmamk_f32 v235, v55, 0x3fb8aa3b, v209
	v_mov_b32_e32 v55, 0xff800000
	v_cndmask_b32_e64 v55, v55, v235, s[54:55]
	s_waitcnt vmcnt(0)
	v_mfma_f32_16x16x32_bf16 v[202:205], v[88:91], v[0:3], 0
	v_mfma_f32_16x16x32_bf16 v[206:209], v[96:99], v[0:3], 0
	v_mfma_f32_16x16x32_bf16 v[202:205], v[92:95], v[4:7], v[202:205]
	v_mfma_f32_16x16x32_bf16 v[206:209], v[100:103], v[4:7], v[206:209]
	s_waitcnt vmcnt(32)
	v_fmamk_f32 v235, v56, 0x3fb8aa3b, v194
	v_mov_b32_e32 v56, 0xff800000
	v_cndmask_b32_e64 v56, v56, v235, s[40:41]
	v_fmamk_f32 v235, v57, 0x3fb8aa3b, v195
	v_mov_b32_e32 v57, 0xff800000
	v_cndmask_b32_e64 v57, v57, v235, s[42:43]
	v_fmamk_f32 v235, v58, 0x3fb8aa3b, v196
	v_mov_b32_e32 v58, 0xff800000
	v_cndmask_b32_e64 v58, v58, v235, s[44:45]
	v_fmamk_f32 v235, v59, 0x3fb8aa3b, v197
	v_mov_b32_e32 v59, 0xff800000
	v_cndmask_b32_e64 v59, v59, v235, s[46:47]
	v_fmamk_f32 v235, v60, 0x3fb8aa3b, v198
	v_mov_b32_e32 v60, 0xff800000
	v_cndmask_b32_e64 v60, v60, v235, s[48:49]
	v_fmamk_f32 v235, v61, 0x3fb8aa3b, v199
	v_mov_b32_e32 v61, 0xff800000
	v_cndmask_b32_e64 v61, v61, v235, s[50:51]
	v_fmamk_f32 v235, v62, 0x3fb8aa3b, v200
	v_mov_b32_e32 v62, 0xff800000
	v_cndmask_b32_e64 v62, v62, v235, s[52:53]
	v_fmamk_f32 v235, v63, 0x3fb8aa3b, v201
	v_mov_b32_e32 v63, 0xff800000
	v_cndmask_b32_e64 v63, v63, v235, s[54:55]
	s_nop 7
	s_waitcnt vmcnt(24)
	v_fmamk_f32 v235, v64, 0x3fb8aa3b, v202
	v_mov_b32_e32 v64, 0xff800000
	v_cndmask_b32_e64 v64, v64, v235, s[40:41]
	v_fmamk_f32 v235, v65, 0x3fb8aa3b, v203
	v_mov_b32_e32 v65, 0xff800000
	v_cndmask_b32_e64 v65, v65, v235, s[42:43]
	v_fmamk_f32 v235, v66, 0x3fb8aa3b, v204
	v_mov_b32_e32 v66, 0xff800000
	v_cndmask_b32_e64 v66, v66, v235, s[44:45]
	v_fmamk_f32 v235, v67, 0x3fb8aa3b, v205
	v_mov_b32_e32 v67, 0xff800000
	v_cndmask_b32_e64 v67, v67, v235, s[46:47]
	v_fmamk_f32 v235, v68, 0x3fb8aa3b, v206
	v_mov_b32_e32 v68, 0xff800000
	v_cndmask_b32_e64 v68, v68, v235, s[48:49]
	v_fmamk_f32 v235, v69, 0x3fb8aa3b, v207
	v_mov_b32_e32 v69, 0xff800000
	v_cndmask_b32_e64 v69, v69, v235, s[50:51]
	v_fmamk_f32 v235, v70, 0x3fb8aa3b, v208
	v_mov_b32_e32 v70, 0xff800000
	v_cndmask_b32_e64 v70, v70, v235, s[52:53]
	v_fmamk_f32 v235, v71, 0x3fb8aa3b, v209
	v_mov_b32_e32 v71, 0xff800000
	v_cndmask_b32_e64 v71, v71, v235, s[54:55]
	v_max3_f32 v233, v8, v9, v10
	v_max_f32_e32 v233, v233, v11
	v_max_f32_e32 v233, v233, v12
	v_max_f32_e32 v233, v233, v13
	v_max_f32_e32 v233, v233, v14
	v_max_f32_e32 v233, v233, v15
	v_max_f32_e32 v233, v233, v16
	v_max_f32_e32 v233, v233, v17
	v_max_f32_e32 v233, v233, v18
	v_max_f32_e32 v233, v233, v19
	v_max_f32_e32 v233, v233, v20
	v_max_f32_e32 v233, v233, v21
	v_max_f32_e32 v233, v233, v22
	v_max_f32_e32 v233, v233, v23
	v_max_f32_e32 v233, v233, v24
	v_max_f32_e32 v233, v233, v25
	v_max_f32_e32 v233, v233, v26
	v_max_f32_e32 v233, v233, v27
	v_max_f32_e32 v233, v233, v28
	v_max_f32_e32 v233, v233, v29
	v_max_f32_e32 v233, v233, v30
	v_max_f32_e32 v233, v233, v31
	v_max_f32_e32 v233, v233, v32
	v_max_f32_e32 v233, v233, v33
	v_max_f32_e32 v233, v233, v34
	v_max_f32_e32 v233, v233, v35
	v_max_f32_e32 v233, v233, v36
	v_max_f32_e32 v233, v233, v37
	v_max_f32_e32 v233, v233, v38
	v_max_f32_e32 v233, v233, v39
	v_max_f32_e32 v233, v233, v40
	v_max_f32_e32 v233, v233, v41
	v_max_f32_e32 v233, v233, v42
	v_max_f32_e32 v233, v233, v43
	v_max_f32_e32 v233, v233, v44
	v_max_f32_e32 v233, v233, v45
	v_max_f32_e32 v233, v233, v46
	v_max_f32_e32 v233, v233, v47
	v_max_f32_e32 v233, v233, v48
	v_max_f32_e32 v233, v233, v49
	v_max_f32_e32 v233, v233, v50
	v_max_f32_e32 v233, v233, v51
	v_max_f32_e32 v233, v233, v52
	v_max_f32_e32 v233, v233, v53
	v_max_f32_e32 v233, v233, v54
	v_max_f32_e32 v233, v233, v55
	v_max_f32_e32 v233, v233, v56
	v_max_f32_e32 v233, v233, v57
	v_max_f32_e32 v233, v233, v58
	v_max_f32_e32 v233, v233, v59
	v_max_f32_e32 v233, v233, v60
	v_max_f32_e32 v233, v233, v61
	v_max_f32_e32 v233, v233, v62
	v_max_f32_e32 v233, v233, v63
	v_max_f32_e32 v233, v233, v64
	v_max_f32_e32 v233, v233, v65
	v_max_f32_e32 v233, v233, v66
	v_max_f32_e32 v233, v233, v67
	v_max_f32_e32 v233, v233, v68
	v_max_f32_e32 v233, v233, v69
	v_max_f32_e32 v233, v233, v70
	v_max_f32_e32 v233, v233, v71
	ds_bpermute_b32 v235, v223, v233
	s_waitcnt lgkmcnt(0)
	v_max_f32_e32 v233, v233, v235
	ds_bpermute_b32 v235, v232, v233
	s_waitcnt lgkmcnt(0)
	v_max_f32_e32 v233, v233, v235
	v_mov_b32_e32 v234, 0
	v_sub_f32_e32 v8, v8, v233
	v_exp_f32_e32 v8, v8
	v_sub_f32_e32 v9, v9, v233
	v_add_f32_e32 v234, v234, v8
	v_exp_f32_e32 v9, v9
	v_sub_f32_e32 v10, v10, v233
	v_add_f32_e32 v234, v234, v9
	v_exp_f32_e32 v10, v10
	v_sub_f32_e32 v11, v11, v233
	v_add_f32_e32 v234, v234, v10
	v_exp_f32_e32 v11, v11
	v_sub_f32_e32 v12, v12, v233
	v_add_f32_e32 v234, v234, v11
	v_exp_f32_e32 v12, v12
	v_sub_f32_e32 v13, v13, v233
	v_add_f32_e32 v234, v234, v12
	v_exp_f32_e32 v13, v13
	v_sub_f32_e32 v14, v14, v233
	v_add_f32_e32 v234, v234, v13
	v_exp_f32_e32 v14, v14
	v_sub_f32_e32 v15, v15, v233
	v_add_f32_e32 v234, v234, v14
	v_exp_f32_e32 v15, v15
	v_sub_f32_e32 v16, v16, v233
	v_add_f32_e32 v234, v234, v15
	v_exp_f32_e32 v16, v16
	v_sub_f32_e32 v17, v17, v233
	v_add_f32_e32 v234, v234, v16
	v_exp_f32_e32 v17, v17
	v_sub_f32_e32 v18, v18, v233
	v_add_f32_e32 v234, v234, v17
	v_exp_f32_e32 v18, v18
	v_sub_f32_e32 v19, v19, v233
	v_add_f32_e32 v234, v234, v18
	v_exp_f32_e32 v19, v19
	v_sub_f32_e32 v20, v20, v233
	v_add_f32_e32 v234, v234, v19
	v_exp_f32_e32 v20, v20
	v_sub_f32_e32 v21, v21, v233
	v_add_f32_e32 v234, v234, v20
	v_exp_f32_e32 v21, v21
	v_sub_f32_e32 v22, v22, v233
	v_add_f32_e32 v234, v234, v21
	v_exp_f32_e32 v22, v22
	v_sub_f32_e32 v23, v23, v233
	v_add_f32_e32 v234, v234, v22
	v_exp_f32_e32 v23, v23
	v_sub_f32_e32 v24, v24, v233
	v_add_f32_e32 v234, v234, v23
	v_exp_f32_e32 v24, v24
	v_sub_f32_e32 v25, v25, v233
	v_add_f32_e32 v234, v234, v24
	v_exp_f32_e32 v25, v25
	v_sub_f32_e32 v26, v26, v233
	v_add_f32_e32 v234, v234, v25
	v_exp_f32_e32 v26, v26
	v_sub_f32_e32 v27, v27, v233
	v_add_f32_e32 v234, v234, v26
	v_exp_f32_e32 v27, v27
	v_sub_f32_e32 v28, v28, v233
	v_add_f32_e32 v234, v234, v27
	v_exp_f32_e32 v28, v28
	v_sub_f32_e32 v29, v29, v233
	v_add_f32_e32 v234, v234, v28
	v_exp_f32_e32 v29, v29
	v_sub_f32_e32 v30, v30, v233
	v_add_f32_e32 v234, v234, v29
	v_exp_f32_e32 v30, v30
	v_sub_f32_e32 v31, v31, v233
	v_add_f32_e32 v234, v234, v30
	v_exp_f32_e32 v31, v31
	v_sub_f32_e32 v32, v32, v233
	v_add_f32_e32 v234, v234, v31
	v_exp_f32_e32 v32, v32
	v_sub_f32_e32 v33, v33, v233
	v_add_f32_e32 v234, v234, v32
	v_exp_f32_e32 v33, v33
	v_sub_f32_e32 v34, v34, v233
	v_add_f32_e32 v234, v234, v33
	v_exp_f32_e32 v34, v34
	v_sub_f32_e32 v35, v35, v233
	v_add_f32_e32 v234, v234, v34
	v_exp_f32_e32 v35, v35
	v_sub_f32_e32 v36, v36, v233
	v_add_f32_e32 v234, v234, v35
	v_exp_f32_e32 v36, v36
	v_sub_f32_e32 v37, v37, v233
	v_add_f32_e32 v234, v234, v36
	v_exp_f32_e32 v37, v37
	v_sub_f32_e32 v38, v38, v233
	v_add_f32_e32 v234, v234, v37
	v_exp_f32_e32 v38, v38
	v_sub_f32_e32 v39, v39, v233
	v_add_f32_e32 v234, v234, v38
	v_exp_f32_e32 v39, v39
	v_sub_f32_e32 v40, v40, v233
	v_add_f32_e32 v234, v234, v39
	v_exp_f32_e32 v40, v40
	v_sub_f32_e32 v41, v41, v233
	v_add_f32_e32 v234, v234, v40
	v_exp_f32_e32 v41, v41
	v_sub_f32_e32 v42, v42, v233
	v_add_f32_e32 v234, v234, v41
	v_exp_f32_e32 v42, v42
	v_sub_f32_e32 v43, v43, v233
	v_add_f32_e32 v234, v234, v42
	v_exp_f32_e32 v43, v43
	v_sub_f32_e32 v44, v44, v233
	v_add_f32_e32 v234, v234, v43
	v_exp_f32_e32 v44, v44
	v_sub_f32_e32 v45, v45, v233
	v_add_f32_e32 v234, v234, v44
	v_exp_f32_e32 v45, v45
	v_sub_f32_e32 v46, v46, v233
	v_add_f32_e32 v234, v234, v45
	v_exp_f32_e32 v46, v46
	v_sub_f32_e32 v47, v47, v233
	v_add_f32_e32 v234, v234, v46
	v_exp_f32_e32 v47, v47
	v_sub_f32_e32 v48, v48, v233
	v_add_f32_e32 v234, v234, v47
	v_exp_f32_e32 v48, v48
	v_sub_f32_e32 v49, v49, v233
	v_add_f32_e32 v234, v234, v48
	v_exp_f32_e32 v49, v49
	v_sub_f32_e32 v50, v50, v233
	v_add_f32_e32 v234, v234, v49
	v_exp_f32_e32 v50, v50
	v_sub_f32_e32 v51, v51, v233
	v_add_f32_e32 v234, v234, v50
	v_exp_f32_e32 v51, v51
	v_sub_f32_e32 v52, v52, v233
	v_add_f32_e32 v234, v234, v51
	v_exp_f32_e32 v52, v52
	v_sub_f32_e32 v53, v53, v233
	v_add_f32_e32 v234, v234, v52
	v_exp_f32_e32 v53, v53
	v_sub_f32_e32 v54, v54, v233
	v_add_f32_e32 v234, v234, v53
	v_exp_f32_e32 v54, v54
	v_sub_f32_e32 v55, v55, v233
	v_add_f32_e32 v234, v234, v54
	v_exp_f32_e32 v55, v55
	v_sub_f32_e32 v56, v56, v233
	v_add_f32_e32 v234, v234, v55
	v_exp_f32_e32 v56, v56
	v_sub_f32_e32 v57, v57, v233
	v_add_f32_e32 v234, v234, v56
	v_exp_f32_e32 v57, v57
	v_sub_f32_e32 v58, v58, v233
	v_add_f32_e32 v234, v234, v57
	v_exp_f32_e32 v58, v58
	v_sub_f32_e32 v59, v59, v233
	v_add_f32_e32 v234, v234, v58
	v_exp_f32_e32 v59, v59
	v_sub_f32_e32 v60, v60, v233
	v_add_f32_e32 v234, v234, v59
	v_exp_f32_e32 v60, v60
	v_sub_f32_e32 v61, v61, v233
	v_add_f32_e32 v234, v234, v60
	v_exp_f32_e32 v61, v61
	v_sub_f32_e32 v62, v62, v233
	v_add_f32_e32 v234, v234, v61
	v_exp_f32_e32 v62, v62
	v_sub_f32_e32 v63, v63, v233
	v_add_f32_e32 v234, v234, v62
	v_exp_f32_e32 v63, v63
	v_sub_f32_e32 v64, v64, v233
	v_add_f32_e32 v234, v234, v63
	v_exp_f32_e32 v64, v64
	v_sub_f32_e32 v65, v65, v233
	v_add_f32_e32 v234, v234, v64
	v_exp_f32_e32 v65, v65
	v_sub_f32_e32 v66, v66, v233
	v_add_f32_e32 v234, v234, v65
	v_exp_f32_e32 v66, v66
	v_sub_f32_e32 v67, v67, v233
	v_add_f32_e32 v234, v234, v66
	v_exp_f32_e32 v67, v67
	v_sub_f32_e32 v68, v68, v233
	v_add_f32_e32 v234, v234, v67
	v_exp_f32_e32 v68, v68
	v_sub_f32_e32 v69, v69, v233
	v_add_f32_e32 v234, v234, v68
	v_exp_f32_e32 v69, v69
	v_sub_f32_e32 v70, v70, v233
	v_add_f32_e32 v234, v234, v69
	v_exp_f32_e32 v70, v70
	v_sub_f32_e32 v71, v71, v233
	v_add_f32_e32 v234, v234, v70
	v_exp_f32_e32 v71, v71
	s_nop 0
	v_add_f32_e32 v234, v234, v71
	ds_bpermute_b32 v235, v223, v234
	v_cvt_pk_bf16_f32 v8, v8, v9
	v_cvt_pk_bf16_f32 v9, v10, v11
	v_cvt_pk_bf16_f32 v10, v12, v13
	v_cvt_pk_bf16_f32 v11, v14, v15
	v_cvt_pk_bf16_f32 v16, v16, v17
	v_cvt_pk_bf16_f32 v17, v18, v19
	v_cvt_pk_bf16_f32 v18, v20, v21
	v_cvt_pk_bf16_f32 v19, v22, v23
	v_cvt_pk_bf16_f32 v24, v24, v25
	v_cvt_pk_bf16_f32 v25, v26, v27
	v_cvt_pk_bf16_f32 v26, v28, v29
	v_cvt_pk_bf16_f32 v27, v30, v31
	v_cvt_pk_bf16_f32 v32, v32, v33
	v_cvt_pk_bf16_f32 v33, v34, v35
	v_cvt_pk_bf16_f32 v34, v36, v37
	v_cvt_pk_bf16_f32 v35, v38, v39
	v_cvt_pk_bf16_f32 v40, v40, v41
	v_cvt_pk_bf16_f32 v41, v42, v43
	v_cvt_pk_bf16_f32 v42, v44, v45
	v_cvt_pk_bf16_f32 v43, v46, v47
	v_cvt_pk_bf16_f32 v48, v48, v49
	v_cvt_pk_bf16_f32 v49, v50, v51
	v_cvt_pk_bf16_f32 v50, v52, v53
	v_cvt_pk_bf16_f32 v51, v54, v55
	v_cvt_pk_bf16_f32 v56, v56, v57
	v_cvt_pk_bf16_f32 v57, v58, v59
	v_cvt_pk_bf16_f32 v58, v60, v61
	v_cvt_pk_bf16_f32 v59, v62, v63
	v_cvt_pk_bf16_f32 v64, v64, v65
	v_cvt_pk_bf16_f32 v65, v66, v67
	v_cvt_pk_bf16_f32 v66, v68, v69
	v_cvt_pk_bf16_f32 v67, v70, v71
	s_waitcnt lgkmcnt(0)
	v_add_f32_e32 v234, v234, v235
	ds_bpermute_b32 v235, v232, v234
	s_waitcnt lgkmcnt(0)
	v_add_f32_e32 v234, v234, v235
	s_waitcnt vmcnt(0)
	s_barrier
	v_mov_b32_e32 v138, v136
	ds_read_b128 v[72:75], v138 offset:16
	ds_read_b128 v[76:79], v138 offset:16400
	ds_read_b128 v[80:83], v138 offset:32784
	ds_read_b128 v[84:87], v138 offset:49168
	v_xor_b32_e32 v138, 128, v136
	ds_read_b128 v[88:91], v138 offset:16
	ds_read_b128 v[92:95], v138 offset:16400
	ds_read_b128 v[96:99], v138 offset:32784
	ds_read_b128 v[100:103], v138 offset:49168
	v_xor_b32_e32 v138, 256, v136
	ds_read_b128 v[104:107], v138 offset:16
	ds_read_b128 v[108:111], v138 offset:16400
	ds_read_b128 v[112:115], v138 offset:32784
	ds_read_b128 v[116:119], v138 offset:49168
	s_waitcnt lgkmcnt(8)
	v_mfma_f32_16x16x32_bf16 v[178:181], v[72:75], v[8:11], v[178:181]
	v_mfma_f32_16x16x32_bf16 v[182:185], v[76:79], v[8:11], v[182:185]
	v_mfma_f32_16x16x32_bf16 v[186:189], v[80:83], v[8:11], v[186:189]
	v_mfma_f32_16x16x32_bf16 v[190:193], v[84:87], v[8:11], v[190:193]
	v_xor_b32_e32 v138, 384, v136
	ds_read_b128 v[120:123], v138 offset:16
	ds_read_b128 v[124:127], v138 offset:16400
	ds_read_b128 v[128:131], v138 offset:32784
	ds_read_b128 v[132:135], v138 offset:49168
	s_waitcnt lgkmcnt(8)
	v_mfma_f32_16x16x32_bf16 v[178:181], v[88:91], v[16:19], v[178:181]
	v_mfma_f32_16x16x32_bf16 v[182:185], v[92:95], v[16:19], v[182:185]
	v_mfma_f32_16x16x32_bf16 v[186:189], v[96:99], v[16:19], v[186:189]
	v_mfma_f32_16x16x32_bf16 v[190:193], v[100:103], v[16:19], v[190:193]
	v_xor_b32_e32 v138, 512, v136
	ds_read_b128 v[146:149], v138 offset:16
	ds_read_b128 v[150:153], v138 offset:16400
	ds_read_b128 v[154:157], v138 offset:32784
	ds_read_b128 v[158:161], v138 offset:49168
	s_waitcnt lgkmcnt(8)
	v_mfma_f32_16x16x32_bf16 v[178:181], v[104:107], v[24:27], v[178:181]
	v_mfma_f32_16x16x32_bf16 v[182:185], v[108:111], v[24:27], v[182:185]
	v_mfma_f32_16x16x32_bf16 v[186:189], v[112:115], v[24:27], v[186:189]
	v_mfma_f32_16x16x32_bf16 v[190:193], v[116:119], v[24:27], v[190:193]
	v_xor_b32_e32 v138, 640, v136
	ds_read_b128 v[162:165], v138 offset:16
	ds_read_b128 v[166:169], v138 offset:16400
	ds_read_b128 v[170:173], v138 offset:32784
	ds_read_b128 v[174:177], v138 offset:49168
	s_waitcnt lgkmcnt(8)
	v_mfma_f32_16x16x32_bf16 v[178:181], v[120:123], v[32:35], v[178:181]
	v_mfma_f32_16x16x32_bf16 v[182:185], v[124:127], v[32:35], v[182:185]
	v_mfma_f32_16x16x32_bf16 v[186:189], v[128:131], v[32:35], v[186:189]
	v_mfma_f32_16x16x32_bf16 v[190:193], v[132:135], v[32:35], v[190:193]
	v_xor_b32_e32 v138, 768, v136
	ds_read_b128 v[12:15], v138 offset:16
	ds_read_b128 v[20:23], v138 offset:16400
	ds_read_b128 v[28:31], v138 offset:32784
	ds_read_b128 v[36:39], v138 offset:49168
	s_waitcnt lgkmcnt(8)
	v_mfma_f32_16x16x32_bf16 v[178:181], v[146:149], v[40:43], v[178:181]
	v_mfma_f32_16x16x32_bf16 v[182:185], v[150:153], v[40:43], v[182:185]
	v_mfma_f32_16x16x32_bf16 v[186:189], v[154:157], v[40:43], v[186:189]
	v_mfma_f32_16x16x32_bf16 v[190:193], v[158:161], v[40:43], v[190:193]
	v_xor_b32_e32 v138, 896, v136
	ds_read_b128 v[44:47], v138 offset:16
	ds_read_b128 v[52:55], v138 offset:16400
	ds_read_b128 v[60:63], v138 offset:32784
	ds_read_b128 v[68:71], v138 offset:49168
	s_waitcnt lgkmcnt(8)
	v_mfma_f32_16x16x32_bf16 v[178:181], v[162:165], v[48:51], v[178:181]
	v_mfma_f32_16x16x32_bf16 v[182:185], v[166:169], v[48:51], v[182:185]
	v_mfma_f32_16x16x32_bf16 v[186:189], v[170:173], v[48:51], v[186:189]
	v_mfma_f32_16x16x32_bf16 v[190:193], v[174:177], v[48:51], v[190:193]
	s_waitcnt lgkmcnt(4)
	v_mfma_f32_16x16x32_bf16 v[178:181], v[12:15], v[56:59], v[178:181]
	v_mfma_f32_16x16x32_bf16 v[182:185], v[20:23], v[56:59], v[182:185]
	v_mfma_f32_16x16x32_bf16 v[186:189], v[28:31], v[56:59], v[186:189]
	v_mfma_f32_16x16x32_bf16 v[190:193], v[36:39], v[56:59], v[190:193]
	s_waitcnt lgkmcnt(0)
	v_mfma_f32_16x16x32_bf16 v[178:181], v[44:47], v[64:67], v[178:181]
	v_mfma_f32_16x16x32_bf16 v[182:185], v[52:55], v[64:67], v[182:185]
	v_mfma_f32_16x16x32_bf16 v[186:189], v[60:63], v[64:67], v[186:189]
	v_mfma_f32_16x16x32_bf16 v[190:193], v[68:71], v[64:67], v[190:193]
	v_div_scale_f32 v235, s[36:37], v234, v234, 1.0
	v_rcp_f32_e32 v236, v235
	s_nop 0
	v_fma_f32 v237, -v235, v236, 1.0
	v_fmac_f32_e32 v236, v237, v236
	v_div_scale_f32 v237, vcc, 1.0, v234, 1.0
	v_mul_f32_e32 v240, v237, v236
	v_fma_f32 v241, -v235, v240, v237
	v_fmac_f32_e32 v240, v241, v236
	v_fma_f32 v235, -v235, v240, v237
	v_div_fmas_f32 v235, v235, v236, v240
	v_div_fixup_f32 v233, v235, v234, 1.0
	s_nop 3
	v_mul_f32_e32 v178, v178, v233
	v_mul_f32_e32 v179, v179, v233
	v_mul_f32_e32 v180, v180, v233
	v_mul_f32_e32 v181, v181, v233
	v_cvt_pk_bf16_f32 v178, v178, v179
	v_cvt_pk_bf16_f32 v179, v180, v181
	global_store_dwordx2 v222, v[178:179], s[32:33]
	v_mul_f32_e32 v182, v182, v233
	v_mul_f32_e32 v183, v183, v233
	v_mul_f32_e32 v184, v184, v233
	v_mul_f32_e32 v185, v185, v233
	v_cvt_pk_bf16_f32 v182, v182, v183
	v_cvt_pk_bf16_f32 v183, v184, v185
	global_store_dwordx2 v222, v[182:183], s[32:33] offset:32
	v_mul_f32_e32 v186, v186, v233
	v_mul_f32_e32 v187, v187, v233
	v_mul_f32_e32 v188, v188, v233
	v_mul_f32_e32 v189, v189, v233
	v_cvt_pk_bf16_f32 v186, v186, v187
	v_cvt_pk_bf16_f32 v187, v188, v189
	global_store_dwordx2 v222, v[186:187], s[32:33] offset:64
	v_mul_f32_e32 v190, v190, v233
	v_mul_f32_e32 v191, v191, v233
	v_mul_f32_e32 v192, v192, v233
	v_mul_f32_e32 v193, v193, v233
	v_cvt_pk_bf16_f32 v190, v190, v191
	v_cvt_pk_bf16_f32 v191, v192, v193
	global_store_dwordx2 v222, v[190:191], s[32:33] offset:96
	s_add_u32 s7, s7, 0x200
	s_add_u32 s14, s14, 1
	s_cmp_lt_u32 s14, 4
	s_cbranch_scc1 .Lna_tile
	v_readlane_b32 s0, v245, 0
	v_readlane_b32 s1, v245, 1
	v_readlane_b32 s2, v245, 2
	v_readlane_b32 s3, v245, 3
	v_readlane_b32 s4, v245, 4
	v_readlane_b32 s5, v245, 5
	v_readlane_b32 s6, v245, 6
	v_readlane_b32 s7, v245, 7
	v_readlane_b32 s8, v245, 8
	v_readlane_b32 s9, v245, 9
	v_readlane_b32 s10, v245, 10
	v_readlane_b32 s11, v245, 11
	v_readlane_b32 s12, v245, 12
	v_readlane_b32 s13, v245, 13
	v_readlane_b32 s14, v245, 14
	v_readlane_b32 s15, v245, 15
	v_readlane_b32 s16, v245, 16
	v_readlane_b32 s17, v245, 17
	v_readlane_b32 s18, v245, 18
	v_readlane_b32 s19, v245, 19
	v_readlane_b32 s20, v245, 20
	v_readlane_b32 s21, v245, 21
	v_readlane_b32 s22, v245, 22
	v_readlane_b32 s23, v245, 23
	v_readlane_b32 s24, v245, 24
	v_readlane_b32 s25, v245, 25
	v_readlane_b32 s26, v245, 26
	v_readlane_b32 s27, v245, 27
	v_readlane_b32 s28, v245, 28
	v_readlane_b32 s29, v245, 29
	v_readlane_b32 s30, v245, 30
	v_readlane_b32 s31, v245, 31
	v_readlane_b32 s32, v245, 32
	v_readlane_b32 s33, v245, 33
	v_readlane_b32 s34, v245, 34
	v_readlane_b32 s35, v245, 35
	v_readlane_b32 s36, v245, 36
	v_readlane_b32 s37, v245, 37
	v_readlane_b32 s38, v245, 38
	v_readlane_b32 s39, v245, 39
	v_readlane_b32 s40, v245, 40
	v_readlane_b32 s41, v245, 41
	v_readlane_b32 s42, v245, 42
	v_readlane_b32 s43, v245, 43
	v_readlane_b32 s44, v245, 44
	v_readlane_b32 s45, v245, 45
	v_readlane_b32 s46, v245, 46
	v_readlane_b32 s47, v245, 47
	v_readlane_b32 s48, v245, 48
	v_readlane_b32 s49, v245, 49
	v_readlane_b32 s50, v245, 50
	v_readlane_b32 s51, v245, 51
	v_readlane_b32 s52, v245, 52
	v_readlane_b32 s53, v245, 53
	v_readlane_b32 s54, v245, 54
	v_readlane_b32 s55, v245, 55
	v_readlane_b32 s56, v245, 56
	v_readlane_b32 s57, v245, 57
	v_readlane_b32 s58, v245, 58
	v_readlane_b32 s59, v245, 59
	v_readlane_b32 s60, v245, 60
	v_readlane_b32 s61, v245, 61
	v_readlane_b32 s62, v245, 62
	v_readlane_b32 s63, v245, 63
	v_readlane_b32 s64, v244, 0
	v_readlane_b32 s65, v244, 1
	v_readlane_b32 s66, v244, 2
	v_readlane_b32 s67, v244, 3
	v_readlane_b32 s68, v244, 4
	v_readlane_b32 s69, v244, 5
	v_readlane_b32 s70, v244, 6
	v_readlane_b32 s71, v244, 7
	v_readlane_b32 s72, v244, 8
	v_readlane_b32 s73, v244, 9
	v_readlane_b32 s74, v244, 10
	v_readlane_b32 s75, v244, 11
	v_readlane_b32 s76, v244, 12
	v_readlane_b32 s77, v244, 13
	v_readlane_b32 s78, v244, 14
	v_readlane_b32 s79, v244, 15
